# SwiGLU epilogues: 74 leftover s_nop 0 between scalar v_mul (from the former packed multiplies) removed; transcendental-to-consumer spacing kept at one instruction
# baseline (speedup 1.0000x reference)
;   DI void operator()(const f32x4 (&acc)[2][2][4][2], const Unit& u, int wr, int wc, int fr, int fq) const {
;     ...
;     const int row0 = u.pm * BM + wr * 64 + fr, col0 = u.pn * HALF + wc * 32 + 8 * fq;
; #pragma unroll
;     for (int ai = 0; ai < 2; ++ai)
; #pragma unroll
;       for (int m = 0; m < 4; ++m) {
;         float a[8];
; #pragma unroll
;         for (int n = 0; n < 2; ++n)
; #pragma unroll
;           for (int e = 0; e < 4; ++e) {
;             float gte = acc[ai][0][m][n][e], up = acc[ai][1][m][n][e];
;             a[n * 4 + e] = gte * __builtin_amdgcn_rcpf(1.f + __builtin_amdgcn_exp2f(-gte * LOG2E)) * up;
;           }
;         *(uint4*)(act + (size_t)(row0 + ai * HALF + m * 16) * FFN + col0) =
;             make_uint4(pack_bf16(a[0], a[1]), pack_bf16(a[2], a[3]), pack_bf16(a[4], a[5]), pack_bf16(a[6], a[7]));
.LBB0_162:
	v_mul_f32_e32 v145, 0xbfb8aa3b, v122
	v_exp_f32_e32 v145, v145
	v_lshl_or_b32 v146, s47, 7, v142
	v_lshl_add_u32 v144, s48, 8, v140
	v_ashrrev_i32_e32 v147, 31, v146
	v_add_f32_e32 v145, 1.0, v145
	v_rcp_f32_e32 v148, v145
	v_mul_f32_e32 v145, 0xbfb8aa3b, v123
	v_exp_f32_e32 v145, v145
	s_movk_i32 s24, 0x1600
	s_and_b64 vcc, exec, s[2:3]
	v_add_f32_e32 v145, 1.0, v145
	v_rcp_f32_e32 v149, v145
	s_mov_b32 s47, s45
	s_mov_b32 s48, s46
	s_mov_b32 s49, s44
	v_mul_f32_e32 v122, v122, v148
	v_mul_f32_e32 v123, v123, v149
	v_mul_f32_e32 v122, v126, v122
	v_mul_f32_e32 v123, v127, v123
	v_mul_f32_e32 v126, 0xbfb8aa3b, v124
	v_mul_f32_e32 v127, 0xbfb8aa3b, v125
	v_exp_f32_e32 v126, v126
	v_exp_f32_e32 v127, v127
	v_add_f32_e32 v126, 1.0, v126
	v_add_f32_e32 v127, 1.0, v127
	v_rcp_f32_e32 v126, v126
	v_rcp_f32_e32 v127, v127
	v_mul_f32_e32 v124, v124, v126
	v_mul_f32_e32 v125, v125, v127
	v_mul_f32_e32 v126, 0xbfb8aa3b, v118
	v_mul_f32_e32 v127, 0xbfb8aa3b, v119
	v_exp_f32_e32 v126, v126
	v_exp_f32_e32 v127, v127
	v_mul_f32_e32 v124, v128, v124
	v_mul_f32_e32 v125, v129, v125
	v_add_f32_e32 v126, 1.0, v126
	v_add_f32_e32 v127, 1.0, v127
	v_rcp_f32_e32 v126, v126
	v_rcp_f32_e32 v127, v127
	v_mul_f32_e32 v118, v118, v126
	v_mul_f32_e32 v119, v119, v127
	v_mul_f32_e32 v114, v114, v118
	v_mul_f32_e32 v115, v115, v119
	v_mul_f32_e32 v118, 0xbfb8aa3b, v120
	v_mul_f32_e32 v119, 0xbfb8aa3b, v121
	v_exp_f32_e32 v118, v118
	v_exp_f32_e32 v119, v119
	v_add_f32_e32 v118, 1.0, v118
	v_add_f32_e32 v119, 1.0, v119
	v_rcp_f32_e32 v118, v118
	v_rcp_f32_e32 v119, v119
	v_mul_f32_e32 v118, v120, v118
	v_mul_f32_e32 v119, v121, v119
	v_mul_f32_e32 v116, v116, v118
	v_mul_f32_e32 v117, v117, v119
	v_cvt_pk_bf16_f32 v120, v114, v115
	v_mov_b64_e32 v[114:115], s[60:61]
	v_cvt_pk_bf16_f32 v118, v122, v123
	v_cvt_pk_bf16_f32 v121, v116, v117
	v_mad_i64_i32 v[122:123], s[22:23], v144, s24, v[114:115]
	v_lshlrev_b64 v[116:117], 1, v[146:147]
	v_cvt_pk_bf16_f32 v119, v124, v125
	v_lshl_add_u64 v[122:123], v[122:123], 0, v[116:117]
	global_store_dwordx4 v[122:123], v[118:121], off
	s_nop 1
	v_mul_f32_e32 v118, 0xbfb8aa3b, v110
	v_mul_f32_e32 v119, 0xbfb8aa3b, v111
	v_exp_f32_e32 v118, v118
	v_exp_f32_e32 v119, v119
	v_add_f32_e32 v118, 1.0, v118
	v_add_f32_e32 v119, 1.0, v119
	v_rcp_f32_e32 v118, v118
	v_rcp_f32_e32 v119, v119
	v_mul_f32_e32 v110, v110, v118
	v_mul_f32_e32 v111, v111, v119
	v_mul_f32_e32 v106, v106, v110
	v_mul_f32_e32 v107, v107, v111
	v_mul_f32_e32 v110, 0xbfb8aa3b, v112
	v_mul_f32_e32 v111, 0xbfb8aa3b, v113
	v_exp_f32_e32 v110, v110
	v_exp_f32_e32 v111, v111
	v_add_f32_e32 v110, 1.0, v110
	v_add_f32_e32 v111, 1.0, v111
	v_rcp_f32_e32 v110, v110
	v_rcp_f32_e32 v111, v111
	v_mul_f32_e32 v110, v112, v110
	v_mul_f32_e32 v111, v113, v111
	v_mul_f32_e32 v108, v108, v110
	v_mul_f32_e32 v109, v109, v111
	v_mul_f32_e32 v110, 0xbfb8aa3b, v102
	v_mul_f32_e32 v111, 0xbfb8aa3b, v103
	v_exp_f32_e32 v110, v110
	v_exp_f32_e32 v111, v111
	v_add_f32_e32 v110, 1.0, v110
	v_add_f32_e32 v111, 1.0, v111
	v_rcp_f32_e32 v110, v110
	v_rcp_f32_e32 v111, v111
	v_mul_f32_e32 v102, v102, v110
	v_mul_f32_e32 v103, v103, v111
	v_mul_f32_e32 v102, v98, v102
	v_mul_f32_e32 v103, v99, v103
	v_mul_f32_e32 v98, 0xbfb8aa3b, v104
	v_mul_f32_e32 v99, 0xbfb8aa3b, v105
	v_exp_f32_e32 v98, v98
	v_exp_f32_e32 v99, v99
	v_add_f32_e32 v98, 1.0, v98
	v_add_f32_e32 v99, 1.0, v99
	v_rcp_f32_e32 v98, v98
	v_rcp_f32_e32 v99, v99
	v_mul_f32_e32 v98, v104, v98
	v_mul_f32_e32 v99, v105, v99
	v_mul_f32_e32 v104, v100, v98
	v_mul_f32_e32 v105, v101, v99
	v_cvt_pk_bf16_f32 v100, v102, v103
	v_or_b32_e32 v102, 16, v144
	v_mad_i64_i32 v[102:103], s[22:23], v102, s24, v[114:115]
	v_cvt_pk_bf16_f32 v98, v106, v107
	v_cvt_pk_bf16_f32 v99, v108, v109
	v_cvt_pk_bf16_f32 v101, v104, v105
	v_lshl_add_u64 v[102:103], v[102:103], 0, v[116:117]
	global_store_dwordx4 v[102:103], v[98:101], off
	s_nop 1
	v_mul_f32_e32 v98, 0xbfb8aa3b, v94
	v_mul_f32_e32 v99, 0xbfb8aa3b, v95
	v_exp_f32_e32 v98, v98
	v_exp_f32_e32 v99, v99
	v_add_f32_e32 v98, 1.0, v98
	v_add_f32_e32 v99, 1.0, v99
	v_rcp_f32_e32 v98, v98
	v_rcp_f32_e32 v99, v99
	v_mul_f32_e32 v94, v94, v98
	v_mul_f32_e32 v95, v95, v99
	v_mul_f32_e32 v90, v90, v94
	v_mul_f32_e32 v91, v91, v95
	v_mul_f32_e32 v94, 0xbfb8aa3b, v96
	v_mul_f32_e32 v95, 0xbfb8aa3b, v97
	v_exp_f32_e32 v94, v94
	v_exp_f32_e32 v95, v95
	v_add_f32_e32 v94, 1.0, v94
	v_add_f32_e32 v95, 1.0, v95
	v_rcp_f32_e32 v94, v94
	v_rcp_f32_e32 v95, v95
	v_mul_f32_e32 v94, v96, v94
	v_mul_f32_e32 v95, v97, v95
	v_mul_f32_e32 v92, v92, v94
	v_mul_f32_e32 v93, v93, v95
	v_mul_f32_e32 v94, 0xbfb8aa3b, v86
	v_mul_f32_e32 v95, 0xbfb8aa3b, v87
	v_exp_f32_e32 v94, v94
	v_exp_f32_e32 v95, v95
	v_add_f32_e32 v94, 1.0, v94
	v_add_f32_e32 v95, 1.0, v95
	v_rcp_f32_e32 v94, v94
	v_rcp_f32_e32 v95, v95
	v_mul_f32_e32 v86, v86, v94
	v_mul_f32_e32 v87, v87, v95
	v_mul_f32_e32 v86, v82, v86
	v_mul_f32_e32 v87, v83, v87
	v_mul_f32_e32 v82, 0xbfb8aa3b, v88
	v_mul_f32_e32 v83, 0xbfb8aa3b, v89
	v_exp_f32_e32 v82, v82
	v_exp_f32_e32 v83, v83
	v_add_f32_e32 v82, 1.0, v82
	v_add_f32_e32 v83, 1.0, v83
	v_rcp_f32_e32 v82, v82
	v_rcp_f32_e32 v83, v83
	v_mul_f32_e32 v82, v88, v82
	v_mul_f32_e32 v83, v89, v83
	v_mul_f32_e32 v88, v84, v82
	v_mul_f32_e32 v89, v85, v83
	v_cvt_pk_bf16_f32 v84, v86, v87
	v_or_b32_e32 v86, 32, v144
	v_mad_i64_i32 v[86:87], s[22:23], v86, s24, v[114:115]
	v_cvt_pk_bf16_f32 v82, v90, v91
	v_cvt_pk_bf16_f32 v83, v92, v93
	v_cvt_pk_bf16_f32 v85, v88, v89
	v_lshl_add_u64 v[86:87], v[86:87], 0, v[116:117]
	global_store_dwordx4 v[86:87], v[82:85], off
	s_nop 1
	v_mul_f32_e32 v82, 0xbfb8aa3b, v78
;   DI void operator()(const f32x4 (&acc)[2][2][4][2], const Unit& u, int wr, int wc, int fr, int fq) const {
;     ...
;         float a[8];
; #pragma unroll
;         for (int n = 0; n < 2; ++n)
; #pragma unroll
;           for (int e = 0; e < 4; ++e) {
;             float gte = acc[ai][0][m][n][e], up = acc[ai][1][m][n][e];
;             a[n * 4 + e] = gte * __builtin_amdgcn_rcpf(1.f + __builtin_amdgcn_exp2f(-gte * LOG2E)) * up;
;           }
;         *(uint4*)(act + (size_t)(row0 + ai * HALF + m * 16) * FFN + col0) =
;             make_uint4(pack_bf16(a[0], a[1]), pack_bf16(a[2], a[3]), pack_bf16(a[4], a[5]), pack_bf16(a[6], a[7]));
	v_mul_f32_e32 v83, 0xbfb8aa3b, v79
	v_exp_f32_e32 v82, v82
	v_exp_f32_e32 v83, v83
	v_add_f32_e32 v82, 1.0, v82
	v_add_f32_e32 v83, 1.0, v83
	v_rcp_f32_e32 v82, v82
	v_rcp_f32_e32 v83, v83
	v_mul_f32_e32 v78, v78, v82
	v_mul_f32_e32 v79, v79, v83
	v_mul_f32_e32 v74, v74, v78
	v_mul_f32_e32 v75, v75, v79
	v_mul_f32_e32 v78, 0xbfb8aa3b, v80
	v_mul_f32_e32 v79, 0xbfb8aa3b, v81
	v_exp_f32_e32 v78, v78
	v_exp_f32_e32 v79, v79
	v_add_f32_e32 v78, 1.0, v78
	v_add_f32_e32 v79, 1.0, v79
	v_rcp_f32_e32 v78, v78
	v_rcp_f32_e32 v79, v79
	v_mul_f32_e32 v78, v80, v78
	v_mul_f32_e32 v79, v81, v79
	v_mul_f32_e32 v76, v76, v78
	v_mul_f32_e32 v77, v77, v79
	v_mul_f32_e32 v78, 0xbfb8aa3b, v70
	v_mul_f32_e32 v79, 0xbfb8aa3b, v71
	v_exp_f32_e32 v78, v78
	v_exp_f32_e32 v79, v79
	v_add_f32_e32 v78, 1.0, v78
	v_add_f32_e32 v79, 1.0, v79
	v_rcp_f32_e32 v78, v78
	v_rcp_f32_e32 v79, v79
	v_mul_f32_e32 v70, v70, v78
	v_mul_f32_e32 v71, v71, v79
	v_mul_f32_e32 v70, v66, v70
	v_mul_f32_e32 v71, v67, v71
	v_mul_f32_e32 v66, 0xbfb8aa3b, v72
	v_mul_f32_e32 v67, 0xbfb8aa3b, v73
	v_exp_f32_e32 v66, v66
	v_exp_f32_e32 v67, v67
	v_add_f32_e32 v66, 1.0, v66
	v_add_f32_e32 v67, 1.0, v67
	v_rcp_f32_e32 v66, v66
	v_rcp_f32_e32 v67, v67
	v_mul_f32_e32 v66, v72, v66
	v_mul_f32_e32 v67, v73, v67
	v_mul_f32_e32 v72, v68, v66
	v_mul_f32_e32 v73, v69, v67
	v_cvt_pk_bf16_f32 v68, v70, v71
	v_or_b32_e32 v70, 48, v144
	v_mad_i64_i32 v[70:71], s[22:23], v70, s24, v[114:115]
	v_cvt_pk_bf16_f32 v66, v74, v75
	v_cvt_pk_bf16_f32 v67, v76, v77
	v_cvt_pk_bf16_f32 v69, v72, v73
	v_lshl_add_u64 v[70:71], v[70:71], 0, v[116:117]
	global_store_dwordx4 v[70:71], v[66:69], off
	s_nop 1
	v_mul_f32_e32 v66, 0xbfb8aa3b, v62
	v_mul_f32_e32 v67, 0xbfb8aa3b, v63
	v_exp_f32_e32 v66, v66
	v_exp_f32_e32 v67, v67
	v_add_u32_e32 v68, 0x80, v144
	v_add_f32_e32 v66, 1.0, v66
	v_add_f32_e32 v67, 1.0, v67
	v_rcp_f32_e32 v66, v66
	v_rcp_f32_e32 v67, v67
	v_mul_f32_e32 v62, v62, v66
	v_mul_f32_e32 v63, v63, v67
	v_mul_f32_e32 v58, v58, v62
	v_mul_f32_e32 v59, v59, v63
	v_mul_f32_e32 v62, 0xbfb8aa3b, v64
	v_mul_f32_e32 v63, 0xbfb8aa3b, v65
	v_exp_f32_e32 v62, v62
	v_exp_f32_e32 v63, v63
	v_add_f32_e32 v62, 1.0, v62
	v_add_f32_e32 v63, 1.0, v63
	v_rcp_f32_e32 v62, v62
	v_rcp_f32_e32 v63, v63
	v_mul_f32_e32 v62, v64, v62
	v_mul_f32_e32 v63, v65, v63
	v_mul_f32_e32 v60, v60, v62
	v_mul_f32_e32 v61, v61, v63
	v_mul_f32_e32 v62, 0xbfb8aa3b, v54
	v_mul_f32_e32 v63, 0xbfb8aa3b, v55
	v_exp_f32_e32 v62, v62
	v_exp_f32_e32 v63, v63
	v_add_f32_e32 v62, 1.0, v62
	v_add_f32_e32 v63, 1.0, v63
	v_rcp_f32_e32 v62, v62
	v_rcp_f32_e32 v63, v63
	v_mul_f32_e32 v54, v54, v62
	v_mul_f32_e32 v55, v55, v63
	v_mul_f32_e32 v54, v50, v54
	v_mul_f32_e32 v55, v51, v55
	v_mul_f32_e32 v50, 0xbfb8aa3b, v56
	v_mul_f32_e32 v51, 0xbfb8aa3b, v57
	v_exp_f32_e32 v50, v50
	v_exp_f32_e32 v51, v51
	v_add_f32_e32 v50, 1.0, v50
	v_add_f32_e32 v51, 1.0, v51
	v_rcp_f32_e32 v50, v50
	v_rcp_f32_e32 v51, v51
	v_mul_f32_e32 v50, v56, v50
	v_mul_f32_e32 v51, v57, v51
	v_mul_f32_e32 v56, v52, v50
	v_mul_f32_e32 v57, v53, v51
	v_cvt_pk_bf16_f32 v52, v54, v55
	v_mad_i64_i32 v[54:55], s[22:23], v68, s24, v[114:115]
	v_cvt_pk_bf16_f32 v50, v58, v59
	v_cvt_pk_bf16_f32 v51, v60, v61
	v_cvt_pk_bf16_f32 v53, v56, v57
	v_lshl_add_u64 v[54:55], v[54:55], 0, v[116:117]
	global_store_dwordx4 v[54:55], v[50:53], off
	s_nop 1
	v_mul_f32_e32 v50, 0xbfb8aa3b, v46
	v_mul_f32_e32 v51, 0xbfb8aa3b, v47
	v_exp_f32_e32 v50, v50
	v_exp_f32_e32 v51, v51
	v_add_f32_e32 v50, 1.0, v50
	v_add_f32_e32 v51, 1.0, v51
	v_rcp_f32_e32 v50, v50
	v_rcp_f32_e32 v51, v51
	v_mul_f32_e32 v46, v46, v50
	v_mul_f32_e32 v47, v47, v51
	v_mul_f32_e32 v42, v42, v46
	v_mul_f32_e32 v43, v43, v47
	v_mul_f32_e32 v46, 0xbfb8aa3b, v48
	v_mul_f32_e32 v47, 0xbfb8aa3b, v49
	v_exp_f32_e32 v46, v46
	v_exp_f32_e32 v47, v47
	v_add_f32_e32 v46, 1.0, v46
	v_add_f32_e32 v47, 1.0, v47
	v_rcp_f32_e32 v46, v46
	v_rcp_f32_e32 v47, v47
	v_mul_f32_e32 v46, v48, v46
	v_mul_f32_e32 v47, v49, v47
	v_mul_f32_e32 v44, v44, v46
	v_mul_f32_e32 v45, v45, v47
	v_mul_f32_e32 v46, 0xbfb8aa3b, v38
	v_mul_f32_e32 v47, 0xbfb8aa3b, v39
	v_exp_f32_e32 v46, v46
	v_exp_f32_e32 v47, v47
	v_add_f32_e32 v46, 1.0, v46
	v_add_f32_e32 v47, 1.0, v47
; template <class Epi, class Sched>
; DI void gemm_phase(LAS unsigned char* lds, const Gemm g, const Sched& S, const Epi& E) {
;     ...
;     if (!has_next) break;
; #pragma unroll
;     for (int a = 0; a < 2; ++a)
; #pragma unroll
;       for (int b = 0; b < 2; ++b)
; #pragma unroll
;         for (int m = 0; m < 4; ++m)
; #pragma unroll
;           for (int n = 0; n < 2; ++n) acc[a][b][m][n] = (f32x4){0.f, 0.f, 0.f, 0.f};
;     cur = nxt; cA = nA; cB = nB; ++ui;
;   DI void operator()(const f32x4 (&acc)[2][2][4][2], const Unit& u, int wr, int wc, int fr, int fq) const {
;     ...
;         float a[8];
; #pragma unroll
;         for (int n = 0; n < 2; ++n)
; #pragma unroll
;           for (int e = 0; e < 4; ++e) {
;             float gte = acc[ai][0][m][n][e], up = acc[ai][1][m][n][e];
;             a[n * 4 + e] = gte * __builtin_amdgcn_rcpf(1.f + __builtin_amdgcn_exp2f(-gte * LOG2E)) * up;
;           }
;         *(uint4*)(act + (size_t)(row0 + ai * HALF + m * 16) * FFN + col0) =
;             make_uint4(pack_bf16(a[0], a[1]), pack_bf16(a[2], a[3]), pack_bf16(a[4], a[5]), pack_bf16(a[6], a[7]));
	v_rcp_f32_e32 v46, v46
	v_rcp_f32_e32 v47, v47
	v_mul_f32_e32 v38, v38, v46
	v_mul_f32_e32 v39, v39, v47
	v_mul_f32_e32 v38, v34, v38
	v_mul_f32_e32 v39, v35, v39
	v_mul_f32_e32 v34, 0xbfb8aa3b, v40
	v_mul_f32_e32 v35, 0xbfb8aa3b, v41
	v_exp_f32_e32 v34, v34
	v_exp_f32_e32 v35, v35
	v_add_f32_e32 v34, 1.0, v34
	v_add_f32_e32 v35, 1.0, v35
	v_rcp_f32_e32 v34, v34
	v_rcp_f32_e32 v35, v35
	v_mul_f32_e32 v34, v40, v34
	v_mul_f32_e32 v35, v41, v35
	v_mul_f32_e32 v40, v36, v34
	v_mul_f32_e32 v41, v37, v35
	v_cvt_pk_bf16_f32 v36, v38, v39
	v_add_u32_e32 v38, 0x90, v144
	v_mad_i64_i32 v[38:39], s[22:23], v38, s24, v[114:115]
	v_cvt_pk_bf16_f32 v34, v42, v43
	v_cvt_pk_bf16_f32 v35, v44, v45
	v_cvt_pk_bf16_f32 v37, v40, v41
	v_lshl_add_u64 v[38:39], v[38:39], 0, v[116:117]
	global_store_dwordx4 v[38:39], v[34:37], off
	s_nop 1
	v_mul_f32_e32 v34, 0xbfb8aa3b, v30
	v_mul_f32_e32 v35, 0xbfb8aa3b, v31
	v_exp_f32_e32 v34, v34
	v_exp_f32_e32 v35, v35
	v_add_f32_e32 v34, 1.0, v34
	v_add_f32_e32 v35, 1.0, v35
	v_rcp_f32_e32 v34, v34
	v_rcp_f32_e32 v35, v35
	v_mul_f32_e32 v30, v30, v34
	v_mul_f32_e32 v31, v31, v35
	v_mul_f32_e32 v26, v26, v30
	v_mul_f32_e32 v27, v27, v31
	v_mul_f32_e32 v30, 0xbfb8aa3b, v32
	v_mul_f32_e32 v31, 0xbfb8aa3b, v33
	v_exp_f32_e32 v30, v30
	v_exp_f32_e32 v31, v31
	v_add_f32_e32 v30, 1.0, v30
	v_add_f32_e32 v31, 1.0, v31
	v_rcp_f32_e32 v30, v30
	v_rcp_f32_e32 v31, v31
	v_mul_f32_e32 v30, v32, v30
	v_mul_f32_e32 v31, v33, v31
	v_mul_f32_e32 v28, v28, v30
	v_mul_f32_e32 v29, v29, v31
	v_mul_f32_e32 v30, 0xbfb8aa3b, v22
	v_mul_f32_e32 v31, 0xbfb8aa3b, v23
	v_exp_f32_e32 v30, v30
	v_exp_f32_e32 v31, v31
	v_add_f32_e32 v30, 1.0, v30
	v_add_f32_e32 v31, 1.0, v31
	v_rcp_f32_e32 v30, v30
	v_rcp_f32_e32 v31, v31
	v_mul_f32_e32 v22, v22, v30
	v_mul_f32_e32 v23, v23, v31
	v_mul_f32_e32 v22, v18, v22
	v_mul_f32_e32 v23, v19, v23
	v_mul_f32_e32 v18, 0xbfb8aa3b, v24
	v_mul_f32_e32 v19, 0xbfb8aa3b, v25
	v_exp_f32_e32 v18, v18
	v_exp_f32_e32 v19, v19
	v_add_f32_e32 v18, 1.0, v18
	v_add_f32_e32 v19, 1.0, v19
	v_rcp_f32_e32 v18, v18
	v_rcp_f32_e32 v19, v19
	v_mul_f32_e32 v18, v24, v18
	v_mul_f32_e32 v19, v25, v19
	v_mul_f32_e32 v24, v20, v18
	v_mul_f32_e32 v25, v21, v19
	v_cvt_pk_bf16_f32 v20, v22, v23
	v_add_u32_e32 v22, 0xa0, v144
	v_mad_i64_i32 v[22:23], s[22:23], v22, s24, v[114:115]
	v_cvt_pk_bf16_f32 v18, v26, v27
	v_cvt_pk_bf16_f32 v19, v28, v29
	v_cvt_pk_bf16_f32 v21, v24, v25
	v_lshl_add_u64 v[22:23], v[22:23], 0, v[116:117]
	global_store_dwordx4 v[22:23], v[18:21], off
	s_nop 1
	v_mul_f32_e32 v18, 0xbfb8aa3b, v14
	v_mul_f32_e32 v19, 0xbfb8aa3b, v15
	v_exp_f32_e32 v18, v18
	v_exp_f32_e32 v19, v19
	v_add_f32_e32 v18, 1.0, v18
	v_add_f32_e32 v19, 1.0, v19
	v_rcp_f32_e32 v18, v18
	v_rcp_f32_e32 v19, v19
	v_mul_f32_e32 v14, v14, v18
	v_mul_f32_e32 v15, v15, v19
	v_mul_f32_e32 v10, v10, v14
	v_mul_f32_e32 v11, v11, v15
	v_mul_f32_e32 v14, 0xbfb8aa3b, v16
	v_mul_f32_e32 v15, 0xbfb8aa3b, v17
	v_exp_f32_e32 v14, v14
	v_exp_f32_e32 v15, v15
	v_add_f32_e32 v14, 1.0, v14
	v_add_f32_e32 v15, 1.0, v15
	v_rcp_f32_e32 v14, v14
	v_rcp_f32_e32 v15, v15
	v_mul_f32_e32 v14, v16, v14
	v_mul_f32_e32 v15, v17, v15
	v_mul_f32_e32 v12, v12, v14
	v_mul_f32_e32 v13, v13, v15
	v_mul_f32_e32 v14, 0xbfb8aa3b, v6
	v_mul_f32_e32 v15, 0xbfb8aa3b, v7
	v_exp_f32_e32 v14, v14
	v_exp_f32_e32 v15, v15
	v_add_f32_e32 v14, 1.0, v14
	v_add_f32_e32 v15, 1.0, v15
	v_rcp_f32_e32 v14, v14
	v_rcp_f32_e32 v15, v15
	v_mul_f32_e32 v6, v6, v14
	v_mul_f32_e32 v7, v7, v15
	v_mul_f32_e32 v6, v2, v6
	v_mul_f32_e32 v7, v3, v7
	v_mul_f32_e32 v2, 0xbfb8aa3b, v8
	v_mul_f32_e32 v3, 0xbfb8aa3b, v9
	v_exp_f32_e32 v2, v2
	v_exp_f32_e32 v3, v3
	v_add_f32_e32 v2, 1.0, v2
	v_add_f32_e32 v3, 1.0, v3
	v_rcp_f32_e32 v2, v2
	v_rcp_f32_e32 v3, v3
	v_mul_f32_e32 v2, v8, v2
	v_mul_f32_e32 v3, v9, v3
	v_mul_f32_e32 v8, v4, v2
	v_mul_f32_e32 v9, v5, v3
	v_cvt_pk_bf16_f32 v4, v6, v7
	v_add_u32_e32 v6, 0xb0, v144
	v_mad_i64_i32 v[6:7], s[22:23], v6, s24, v[114:115]
	v_cvt_pk_bf16_f32 v2, v10, v11
	v_cvt_pk_bf16_f32 v3, v12, v13
	v_cvt_pk_bf16_f32 v5, v8, v9
	v_lshl_add_u64 v[6:7], v[6:7], 0, v[116:117]
	s_mov_b64 s[24:25], s[20:21]
	s_mov_b64 s[22:23], s[18:19]
	global_store_dwordx4 v[6:7], v[2:5], off
	s_cbranch_vccnz .LBB0_179

;   DI void operator()(const f32x4 (&acc)[2][2][4][2], const Unit& u, int wr, int wc, int fr, int fq) const {
;     asm volatile("" ::: "memory");
;     const int row0 = u.pm * BM + wr * 64 + fr, col0 = u.pn * HALF + wc * 32 + 8 * fq;
; #pragma unroll
;     for (int ai = 0; ai < 2; ++ai)
; #pragma unroll
;       for (int m = 0; m < 4; ++m) {
;         float a[8];
; #pragma unroll
;         for (int n = 0; n < 2; ++n)
; #pragma unroll
;           for (int e = 0; e < 4; ++e) {
;             float gte = acc[ai][0][m][n][e], up = acc[ai][1][m][n][e];
;             a[n * 4 + e] = gte * __builtin_amdgcn_rcpf(1.f + __builtin_amdgcn_exp2f(-gte * LOG2E)) * up;
;           }
;         *(uint4*)(act + (size_t)(row0 + ai * HALF + m * 16) * FFN + col0) =
;             make_uint4(pack_bf16(a[0], a[1]), pack_bf16(a[2], a[3]), pack_bf16(a[4], a[5]), pack_bf16(a[6], a[7]));
.LBB0_192:
	v_mul_f32_e32 v0, 0xbfb8aa3b, v126
	v_exp_f32_e32 v130, v0
	v_mul_f32_e32 v0, 0xbfb8aa3b, v127
	v_exp_f32_e32 v131, v0
	v_readlane_b32 s0, v253, 12
	v_add_f32_e32 v130, 1.0, v130
	v_rcp_f32_e32 v130, v130
	v_add_f32_e32 v131, 1.0, v131
	v_rcp_f32_e32 v131, v131
	v_add_u32_e32 v0, s0, v141
	v_readlane_b32 s0, v253, 5
	s_movk_i32 s2, 0x1600
	v_mul_f32_e32 v126, v126, v130
	v_mul_f32_e32 v127, v127, v131
	v_mul_f32_e32 v130, 0xbfb8aa3b, v128
	v_mul_f32_e32 v131, 0xbfb8aa3b, v129
	v_exp_f32_e32 v130, v130
	v_exp_f32_e32 v131, v131
	v_mul_f32_e32 v122, v122, v126
	v_mul_f32_e32 v123, v123, v127
	v_or_b32_e32 v132, s0, v140
	v_add_f32_e32 v126, 1.0, v130
	v_add_f32_e32 v127, 1.0, v131
	v_mul_f32_e32 v130, 0xbfb8aa3b, v118
	v_mul_f32_e32 v131, 0xbfb8aa3b, v119
	v_rcp_f32_e32 v126, v126
	v_rcp_f32_e32 v127, v127
	v_exp_f32_e32 v130, v130
	v_exp_f32_e32 v131, v131
	v_readlane_b32 s0, v252, 44
	v_mul_f32_e32 v126, v128, v126
	v_mul_f32_e32 v127, v129, v127
	v_add_f32_e32 v128, 1.0, v130
	v_add_f32_e32 v129, 1.0, v131
	v_mul_f32_e32 v130, 0xbfb8aa3b, v120
	v_mul_f32_e32 v131, 0xbfb8aa3b, v121
	v_exp_f32_e32 v130, v130
	v_exp_f32_e32 v131, v131
	v_rcp_f32_e32 v128, v128
	v_rcp_f32_e32 v129, v129
	v_add_f32_e32 v130, 1.0, v130
	v_add_f32_e32 v131, 1.0, v131
	v_rcp_f32_e32 v130, v130
	v_rcp_f32_e32 v131, v131
	v_mul_f32_e32 v118, v118, v128
	v_mul_f32_e32 v119, v119, v129
	v_or_b32_e32 v132, s21, v132
	v_mul_f32_e32 v114, v114, v118
	v_mul_f32_e32 v115, v115, v119
	v_mul_f32_e32 v118, v120, v130
	v_mul_f32_e32 v119, v121, v131
	v_mul_f32_e32 v124, v124, v126
	v_mul_f32_e32 v125, v125, v127
	v_mul_f32_e32 v116, v116, v118
	v_mul_f32_e32 v117, v117, v119
	v_readlane_b32 s1, v252, 45
	v_cvt_pk_bf16_f32 v121, v116, v117
	v_mul_f32_e32 v116, 0xbfb8aa3b, v110
	v_exp_f32_e32 v116, v116
	v_mul_f32_e32 v117, 0xbfb8aa3b, v111
	v_exp_f32_e32 v117, v117
	v_ashrrev_i32_e32 v133, 31, v132
	v_add_f32_e32 v116, 1.0, v116
	v_cvt_pk_bf16_f32 v119, v124, v125
	v_cvt_pk_bf16_f32 v120, v114, v115
	v_mov_b64_e32 v[114:115], s[0:1]
	v_rcp_f32_e32 v124, v116
	v_add_f32_e32 v116, 1.0, v117
	v_cvt_pk_bf16_f32 v118, v122, v123
	v_mad_i64_i32 v[122:123], s[0:1], v0, s2, v[114:115]
	v_rcp_f32_e32 v125, v116
	v_lshlrev_b64 v[116:117], 1, v[132:133]
	v_lshl_add_u64 v[122:123], v[122:123], 0, v[116:117]
	global_store_dwordx4 v[122:123], v[118:121], off
	v_mul_f32_e32 v110, v110, v124
	v_mul_f32_e32 v111, v111, v125
	s_cmpk_lt_u32 s20, 0x100
	v_mul_f32_e32 v118, 0xbfb8aa3b, v112
	v_mul_f32_e32 v119, 0xbfb8aa3b, v113
	v_exp_f32_e32 v118, v118
	v_exp_f32_e32 v119, v119
	v_mul_f32_e32 v106, v106, v110
	v_mul_f32_e32 v107, v107, v111
	s_mov_b64 s[22:23], 0x3000
	v_add_f32_e32 v110, 1.0, v118
	v_add_f32_e32 v111, 1.0, v119
	v_mul_f32_e32 v118, 0xbfb8aa3b, v102
	v_mul_f32_e32 v119, 0xbfb8aa3b, v103
	v_rcp_f32_e32 v110, v110
	v_rcp_f32_e32 v111, v111
	v_exp_f32_e32 v118, v118
	v_exp_f32_e32 v119, v119
	v_mul_f32_e32 v110, v112, v110
	v_mul_f32_e32 v111, v113, v111
	v_add_f32_e32 v112, 1.0, v118
	v_add_f32_e32 v113, 1.0, v119
	v_mul_f32_e32 v118, 0xbfb8aa3b, v104
	v_mul_f32_e32 v119, 0xbfb8aa3b, v105
	v_exp_f32_e32 v118, v118
	v_exp_f32_e32 v119, v119
	v_rcp_f32_e32 v112, v112
	v_rcp_f32_e32 v113, v113
	v_add_f32_e32 v118, 1.0, v118
	v_add_f32_e32 v119, 1.0, v119
	v_rcp_f32_e32 v118, v118
	v_rcp_f32_e32 v119, v119
	v_mul_f32_e32 v102, v102, v112
	v_mul_f32_e32 v103, v103, v113
	v_mul_f32_e32 v108, v108, v110
	v_mul_f32_e32 v109, v109, v111
	v_mul_f32_e32 v102, v98, v102
	v_mul_f32_e32 v103, v99, v103
	v_mul_f32_e32 v98, v104, v118
	v_mul_f32_e32 v99, v105, v119
	v_mul_f32_e32 v104, v100, v98
	v_mul_f32_e32 v105, v101, v99
	v_cvt_pk_bf16_f32 v100, v102, v103
	v_mul_f32_e32 v102, 0xbfb8aa3b, v94
	v_mul_f32_e32 v103, 0xbfb8aa3b, v95
	v_exp_f32_e32 v102, v102
	v_exp_f32_e32 v103, v103
	v_cvt_pk_bf16_f32 v101, v104, v105
	v_or_b32_e32 v104, 16, v0
	v_mad_i64_i32 v[104:105], s[0:1], v104, s2, v[114:115]
	v_cvt_pk_bf16_f32 v98, v106, v107
	v_cvt_pk_bf16_f32 v99, v108, v109
	v_add_f32_e32 v102, 1.0, v102
	v_add_f32_e32 v103, 1.0, v103
	v_lshl_add_u64 v[104:105], v[104:105], 0, v[116:117]
	v_rcp_f32_e32 v102, v102
	v_rcp_f32_e32 v103, v103
	global_store_dwordx4 v[104:105], v[98:101], off
	v_mul_f32_e32 v94, v94, v102
	v_mul_f32_e32 v95, v95, v103
	v_mul_f32_e32 v98, 0xbfb8aa3b, v96
	v_mul_f32_e32 v99, 0xbfb8aa3b, v97
	v_exp_f32_e32 v98, v98
	v_exp_f32_e32 v99, v99
	v_mul_f32_e32 v90, v90, v94
	v_mul_f32_e32 v91, v91, v95
	v_add_f32_e32 v94, 1.0, v98
	v_add_f32_e32 v95, 1.0, v99
	v_mul_f32_e32 v98, 0xbfb8aa3b, v86
	v_mul_f32_e32 v99, 0xbfb8aa3b, v87
	v_rcp_f32_e32 v94, v94
	v_rcp_f32_e32 v95, v95
	v_exp_f32_e32 v98, v98
	v_exp_f32_e32 v99, v99
	v_mul_f32_e32 v94, v96, v94
	v_mul_f32_e32 v95, v97, v95
	v_add_f32_e32 v96, 1.0, v98
	v_add_f32_e32 v97, 1.0, v99
	v_mul_f32_e32 v98, 0xbfb8aa3b, v88
	v_mul_f32_e32 v99, 0xbfb8aa3b, v89
	v_exp_f32_e32 v98, v98
	v_exp_f32_e32 v99, v99
	v_rcp_f32_e32 v96, v96
	v_rcp_f32_e32 v97, v97
	v_add_f32_e32 v98, 1.0, v98
	v_add_f32_e32 v99, 1.0, v99
	v_rcp_f32_e32 v98, v98
	v_rcp_f32_e32 v99, v99
	v_mul_f32_e32 v86, v86, v96
	v_mul_f32_e32 v87, v87, v97
	v_mul_f32_e32 v92, v92, v94
	v_mul_f32_e32 v93, v93, v95
	v_mul_f32_e32 v86, v82, v86
	v_mul_f32_e32 v87, v83, v87
	v_mul_f32_e32 v82, v88, v98
	v_mul_f32_e32 v83, v89, v99
	v_mul_f32_e32 v88, v84, v82
	v_mul_f32_e32 v89, v85, v83
	v_cvt_pk_bf16_f32 v84, v86, v87
	v_mul_f32_e32 v86, 0xbfb8aa3b, v78
	v_mul_f32_e32 v87, 0xbfb8aa3b, v79
	v_exp_f32_e32 v86, v86
	v_exp_f32_e32 v87, v87
	v_cvt_pk_bf16_f32 v85, v88, v89
	v_or_b32_e32 v88, 32, v0
	v_mad_i64_i32 v[88:89], s[0:1], v88, s2, v[114:115]
;   DI void operator()(const f32x4 (&acc)[2][2][4][2], const Unit& u, int wr, int wc, int fr, int fq) const {
;     ...
;         float a[8];
; #pragma unroll
;         for (int n = 0; n < 2; ++n)
; #pragma unroll
;           for (int e = 0; e < 4; ++e) {
;             float gte = acc[ai][0][m][n][e], up = acc[ai][1][m][n][e];
;             a[n * 4 + e] = gte * __builtin_amdgcn_rcpf(1.f + __builtin_amdgcn_exp2f(-gte * LOG2E)) * up;
;           }
;         *(uint4*)(act + (size_t)(row0 + ai * HALF + m * 16) * FFN + col0) =
;             make_uint4(pack_bf16(a[0], a[1]), pack_bf16(a[2], a[3]), pack_bf16(a[4], a[5]), pack_bf16(a[6], a[7]));
	v_cvt_pk_bf16_f32 v82, v90, v91
	v_cvt_pk_bf16_f32 v83, v92, v93
	v_add_f32_e32 v86, 1.0, v86
	v_add_f32_e32 v87, 1.0, v87
	v_lshl_add_u64 v[88:89], v[88:89], 0, v[116:117]
	v_rcp_f32_e32 v86, v86
	v_rcp_f32_e32 v87, v87
	global_store_dwordx4 v[88:89], v[82:85], off
	v_mul_f32_e32 v78, v78, v86
	v_mul_f32_e32 v79, v79, v87
	v_mul_f32_e32 v82, 0xbfb8aa3b, v80
	v_mul_f32_e32 v83, 0xbfb8aa3b, v81
	v_exp_f32_e32 v82, v82
	v_exp_f32_e32 v83, v83
	v_mul_f32_e32 v74, v74, v78
	v_mul_f32_e32 v75, v75, v79
	v_add_f32_e32 v78, 1.0, v82
	v_add_f32_e32 v79, 1.0, v83
	v_mul_f32_e32 v82, 0xbfb8aa3b, v70
	v_mul_f32_e32 v83, 0xbfb8aa3b, v71
	v_rcp_f32_e32 v78, v78
	v_rcp_f32_e32 v79, v79
	v_exp_f32_e32 v82, v82
	v_exp_f32_e32 v83, v83
	v_mul_f32_e32 v78, v80, v78
	v_mul_f32_e32 v79, v81, v79
	v_add_f32_e32 v80, 1.0, v82
	v_add_f32_e32 v81, 1.0, v83
	v_mul_f32_e32 v82, 0xbfb8aa3b, v72
	v_mul_f32_e32 v83, 0xbfb8aa3b, v73
	v_exp_f32_e32 v82, v82
	v_exp_f32_e32 v83, v83
	v_rcp_f32_e32 v80, v80
	v_rcp_f32_e32 v81, v81
	v_add_f32_e32 v82, 1.0, v82
	v_add_f32_e32 v83, 1.0, v83
	v_rcp_f32_e32 v82, v82
	v_rcp_f32_e32 v83, v83
	v_mul_f32_e32 v70, v70, v80
	v_mul_f32_e32 v71, v71, v81
	v_mul_f32_e32 v76, v76, v78
	v_mul_f32_e32 v77, v77, v79
	v_mul_f32_e32 v70, v66, v70
	v_mul_f32_e32 v71, v67, v71
	v_mul_f32_e32 v66, v72, v82
	v_mul_f32_e32 v67, v73, v83
	v_mul_f32_e32 v72, v68, v66
	v_mul_f32_e32 v73, v69, v67
	v_cvt_pk_bf16_f32 v68, v70, v71
	v_mul_f32_e32 v71, 0xbfb8aa3b, v62
	v_cvt_pk_bf16_f32 v69, v72, v73
	v_exp_f32_e32 v72, v71
	v_mul_f32_e32 v71, 0xbfb8aa3b, v63
	v_exp_f32_e32 v73, v71
	v_or_b32_e32 v70, 48, v0
	v_mad_i64_i32 v[70:71], s[0:1], v70, s2, v[114:115]
	v_cvt_pk_bf16_f32 v66, v74, v75
	v_cvt_pk_bf16_f32 v67, v76, v77
	v_add_f32_e32 v72, 1.0, v72
	v_add_f32_e32 v73, 1.0, v73
	v_lshl_add_u64 v[70:71], v[70:71], 0, v[116:117]
	v_rcp_f32_e32 v72, v72
	v_rcp_f32_e32 v73, v73
	global_store_dwordx4 v[70:71], v[66:69], off
	v_mul_f32_e32 v62, v62, v72
	v_mul_f32_e32 v63, v63, v73
	v_mul_f32_e32 v66, 0xbfb8aa3b, v64
	v_mul_f32_e32 v67, 0xbfb8aa3b, v65
	v_exp_f32_e32 v66, v66
	v_exp_f32_e32 v67, v67
	v_mul_f32_e32 v58, v58, v62
	v_mul_f32_e32 v59, v59, v63
	v_add_u32_e32 v68, 0x80, v0
	v_add_f32_e32 v62, 1.0, v66
	v_add_f32_e32 v63, 1.0, v67
	v_mul_f32_e32 v66, 0xbfb8aa3b, v54
	v_mul_f32_e32 v67, 0xbfb8aa3b, v55
	v_rcp_f32_e32 v62, v62
	v_rcp_f32_e32 v63, v63
	v_exp_f32_e32 v66, v66
	v_exp_f32_e32 v67, v67
	v_mul_f32_e32 v62, v64, v62
	v_mul_f32_e32 v63, v65, v63
	v_add_f32_e32 v64, 1.0, v66
	v_add_f32_e32 v65, 1.0, v67
	v_mul_f32_e32 v66, 0xbfb8aa3b, v56
	v_mul_f32_e32 v67, 0xbfb8aa3b, v57
	v_exp_f32_e32 v66, v66
	v_exp_f32_e32 v67, v67
	v_rcp_f32_e32 v64, v64
	v_rcp_f32_e32 v65, v65
	v_add_f32_e32 v66, 1.0, v66
	v_add_f32_e32 v67, 1.0, v67
	v_rcp_f32_e32 v66, v66
	v_rcp_f32_e32 v67, v67
	v_mul_f32_e32 v54, v54, v64
	v_mul_f32_e32 v55, v55, v65
	v_mul_f32_e32 v60, v60, v62
	v_mul_f32_e32 v61, v61, v63
	v_mul_f32_e32 v54, v50, v54
	v_mul_f32_e32 v55, v51, v55
	v_mul_f32_e32 v50, v56, v66
	v_mul_f32_e32 v51, v57, v67
	v_mul_f32_e32 v56, v52, v50
	v_mul_f32_e32 v57, v53, v51
	v_mul_f32_e32 v53, 0xbfb8aa3b, v46
	v_cvt_pk_bf16_f32 v52, v54, v55
	v_exp_f32_e32 v54, v53
	v_mul_f32_e32 v53, 0xbfb8aa3b, v47
	v_exp_f32_e32 v55, v53
	v_cvt_pk_bf16_f32 v53, v56, v57
	v_mad_i64_i32 v[56:57], s[0:1], v68, s2, v[114:115]
	v_cvt_pk_bf16_f32 v50, v58, v59
	v_cvt_pk_bf16_f32 v51, v60, v61
	v_add_f32_e32 v54, 1.0, v54
	v_add_f32_e32 v55, 1.0, v55
	v_lshl_add_u64 v[56:57], v[56:57], 0, v[116:117]
	v_rcp_f32_e32 v54, v54
	v_rcp_f32_e32 v55, v55
	global_store_dwordx4 v[56:57], v[50:53], off
	v_mul_f32_e32 v46, v46, v54
	v_mul_f32_e32 v47, v47, v55
	v_mul_f32_e32 v50, 0xbfb8aa3b, v48
	v_mul_f32_e32 v51, 0xbfb8aa3b, v49
	v_exp_f32_e32 v50, v50
	v_exp_f32_e32 v51, v51
	v_mul_f32_e32 v42, v42, v46
	v_mul_f32_e32 v43, v43, v47
	v_add_f32_e32 v46, 1.0, v50
	v_add_f32_e32 v47, 1.0, v51
	v_mul_f32_e32 v50, 0xbfb8aa3b, v38
	v_mul_f32_e32 v51, 0xbfb8aa3b, v39
	v_rcp_f32_e32 v46, v46
	v_rcp_f32_e32 v47, v47
	v_exp_f32_e32 v50, v50
	v_exp_f32_e32 v51, v51
	v_mul_f32_e32 v46, v48, v46
	v_mul_f32_e32 v47, v49, v47
	v_add_f32_e32 v48, 1.0, v50
	v_add_f32_e32 v49, 1.0, v51
	v_mul_f32_e32 v50, 0xbfb8aa3b, v40
; #define PG8_WAIT_V(n) asm volatile("s_waitcnt vmcnt(" #n ")" ::: "memory")
; #define PG8_BAR __builtin_amdgcn_s_barrier()
; template <class Epi, class Sched>
; DI void gemm_phase(LAS unsigned char* lds, const Gemm g, const Sched& S, const Epi& E) {
;     ...
;   PG8_WAIT_V(0);
;   if (wr == 0) PG8_BAR;
;   PG8_BAR;
;   DI void operator()(const f32x4 (&acc)[2][2][4][2], const Unit& u, int wr, int wc, int fr, int fq) const {
;     ...
;         float a[8];
; #pragma unroll
;         for (int n = 0; n < 2; ++n)
; #pragma unroll
;           for (int e = 0; e < 4; ++e) {
;             float gte = acc[ai][0][m][n][e], up = acc[ai][1][m][n][e];
;             a[n * 4 + e] = gte * __builtin_amdgcn_rcpf(1.f + __builtin_amdgcn_exp2f(-gte * LOG2E)) * up;
;           }
;         *(uint4*)(act + (size_t)(row0 + ai * HALF + m * 16) * FFN + col0) =
;             make_uint4(pack_bf16(a[0], a[1]), pack_bf16(a[2], a[3]), pack_bf16(a[4], a[5]), pack_bf16(a[6], a[7]));
	v_mul_f32_e32 v51, 0xbfb8aa3b, v41
	v_exp_f32_e32 v50, v50
	v_exp_f32_e32 v51, v51
	v_rcp_f32_e32 v48, v48
	v_rcp_f32_e32 v49, v49
	v_add_f32_e32 v50, 1.0, v50
	v_add_f32_e32 v51, 1.0, v51
	v_rcp_f32_e32 v50, v50
	v_rcp_f32_e32 v51, v51
	v_mul_f32_e32 v38, v38, v48
	v_mul_f32_e32 v39, v39, v49
	v_mul_f32_e32 v44, v44, v46
	v_mul_f32_e32 v45, v45, v47
	v_mul_f32_e32 v38, v34, v38
	v_mul_f32_e32 v39, v35, v39
	v_mul_f32_e32 v34, v40, v50
	v_mul_f32_e32 v35, v41, v51
	v_mul_f32_e32 v40, v36, v34
	v_mul_f32_e32 v41, v37, v35
	v_cvt_pk_bf16_f32 v36, v38, v39
	v_mul_f32_e32 v38, 0xbfb8aa3b, v30
	v_mul_f32_e32 v39, 0xbfb8aa3b, v31
	v_exp_f32_e32 v38, v38
	v_exp_f32_e32 v39, v39
	v_cvt_pk_bf16_f32 v37, v40, v41
	v_add_u32_e32 v40, 0x90, v0
	v_mad_i64_i32 v[40:41], s[0:1], v40, s2, v[114:115]
	v_cvt_pk_bf16_f32 v34, v42, v43
	v_cvt_pk_bf16_f32 v35, v44, v45
	v_add_f32_e32 v38, 1.0, v38
	v_add_f32_e32 v39, 1.0, v39
	v_lshl_add_u64 v[40:41], v[40:41], 0, v[116:117]
	v_rcp_f32_e32 v38, v38
	v_rcp_f32_e32 v39, v39
	global_store_dwordx4 v[40:41], v[34:37], off
	v_mul_f32_e32 v30, v30, v38
	v_mul_f32_e32 v31, v31, v39
	v_mul_f32_e32 v34, 0xbfb8aa3b, v32
	v_mul_f32_e32 v35, 0xbfb8aa3b, v33
	v_exp_f32_e32 v34, v34
	v_exp_f32_e32 v35, v35
	v_mul_f32_e32 v26, v26, v30
	v_mul_f32_e32 v27, v27, v31
	v_add_f32_e32 v30, 1.0, v34
	v_add_f32_e32 v31, 1.0, v35
	v_mul_f32_e32 v34, 0xbfb8aa3b, v22
	v_mul_f32_e32 v35, 0xbfb8aa3b, v23
	v_rcp_f32_e32 v30, v30
	v_rcp_f32_e32 v31, v31
	v_exp_f32_e32 v34, v34
	v_exp_f32_e32 v35, v35
	v_mul_f32_e32 v30, v32, v30
	v_mul_f32_e32 v31, v33, v31
	v_add_f32_e32 v32, 1.0, v34
	v_add_f32_e32 v33, 1.0, v35
	v_mul_f32_e32 v34, 0xbfb8aa3b, v24
	v_mul_f32_e32 v35, 0xbfb8aa3b, v25
	v_exp_f32_e32 v34, v34
	v_exp_f32_e32 v35, v35
	v_rcp_f32_e32 v32, v32
	v_rcp_f32_e32 v33, v33
	v_add_f32_e32 v34, 1.0, v34
	v_add_f32_e32 v35, 1.0, v35
	v_rcp_f32_e32 v34, v34
	v_rcp_f32_e32 v35, v35
	v_mul_f32_e32 v22, v22, v32
	v_mul_f32_e32 v23, v23, v33
	v_mul_f32_e32 v28, v28, v30
	v_mul_f32_e32 v29, v29, v31
	v_mul_f32_e32 v22, v18, v22
	v_mul_f32_e32 v23, v19, v23
	v_mul_f32_e32 v18, v24, v34
	v_mul_f32_e32 v19, v25, v35
	v_mul_f32_e32 v24, v20, v18
	v_mul_f32_e32 v25, v21, v19
	v_cvt_pk_bf16_f32 v20, v22, v23
	v_mul_f32_e32 v22, 0xbfb8aa3b, v14
	v_mul_f32_e32 v23, 0xbfb8aa3b, v15
	v_exp_f32_e32 v22, v22
	v_exp_f32_e32 v23, v23
	v_cvt_pk_bf16_f32 v21, v24, v25
	v_add_u32_e32 v24, 0xa0, v0
	v_mad_i64_i32 v[24:25], s[0:1], v24, s2, v[114:115]
	v_cvt_pk_bf16_f32 v18, v26, v27
	v_cvt_pk_bf16_f32 v19, v28, v29
	v_add_f32_e32 v22, 1.0, v22
	v_add_f32_e32 v23, 1.0, v23
	v_lshl_add_u64 v[24:25], v[24:25], 0, v[116:117]
	v_rcp_f32_e32 v22, v22
	v_rcp_f32_e32 v23, v23
	global_store_dwordx4 v[24:25], v[18:21], off
	v_add_u32_e32 v0, 0xb0, v0
	v_mul_f32_e32 v14, v14, v22
	v_mul_f32_e32 v15, v15, v23
	v_mul_f32_e32 v18, 0xbfb8aa3b, v16
	v_mul_f32_e32 v19, 0xbfb8aa3b, v17
	v_exp_f32_e32 v18, v18
	v_exp_f32_e32 v19, v19
	v_mul_f32_e32 v10, v10, v14
	v_mul_f32_e32 v11, v11, v15
	v_add_f32_e32 v14, 1.0, v18
	v_add_f32_e32 v15, 1.0, v19
	v_mul_f32_e32 v18, 0xbfb8aa3b, v6
	v_mul_f32_e32 v19, 0xbfb8aa3b, v7
	v_rcp_f32_e32 v14, v14
	v_rcp_f32_e32 v15, v15
	v_exp_f32_e32 v18, v18
	v_exp_f32_e32 v19, v19
	v_mul_f32_e32 v14, v16, v14
	v_mul_f32_e32 v15, v17, v15
	v_add_f32_e32 v16, 1.0, v18
	v_add_f32_e32 v17, 1.0, v19
	v_mul_f32_e32 v18, 0xbfb8aa3b, v8
	v_mul_f32_e32 v19, 0xbfb8aa3b, v9
	v_exp_f32_e32 v18, v18
	v_exp_f32_e32 v19, v19
	v_rcp_f32_e32 v16, v16
	v_rcp_f32_e32 v17, v17
	v_add_f32_e32 v18, 1.0, v18
	v_add_f32_e32 v19, 1.0, v19
	v_rcp_f32_e32 v18, v18
	v_rcp_f32_e32 v19, v19
	v_mul_f32_e32 v6, v6, v16
	v_mul_f32_e32 v7, v7, v17
	v_mul_f32_e32 v12, v12, v14
	v_mul_f32_e32 v13, v13, v15
	v_mul_f32_e32 v6, v2, v6
	v_mul_f32_e32 v7, v3, v7
	v_mul_f32_e32 v2, v8, v18
	v_mul_f32_e32 v3, v9, v19
	v_mul_f32_e32 v8, v4, v2
	v_mul_f32_e32 v9, v5, v3
	v_cvt_pk_bf16_f32 v4, v6, v7
	v_mad_i64_i32 v[6:7], s[0:1], v0, s2, v[114:115]
	v_cvt_pk_bf16_f32 v2, v10, v11
	v_cvt_pk_bf16_f32 v3, v12, v13
	v_cvt_pk_bf16_f32 v5, v8, v9
	v_lshl_add_u64 v[6:7], v[6:7], 0, v[116:117]
	global_store_dwordx4 v[6:7], v[2:5], off
	s_waitcnt vmcnt(0)
	s_cbranch_scc0 .LBB0_194
	s_barrier
